# K-loop: removed the 4 redundant post-barrier s_waitcnt lgkmcnt(0) in front of each MFMA block (pre-barrier drain kept), on top of v72
# baseline (speedup 1.0000x reference)
; #define PG8_STAGE(bufoff, gbase, voff) do { _Pragma("unroll") for (int _i = 0; _i < 2; ++_i) \
;         __builtin_amdgcn_global_load_lds((const unsigned*)((const char*)(gbase) + (voff)[_i]), (PG8_LAS unsigned*)(lds + (bufoff) + ldsw + _i * 8192), 16, 0, 0); } while (0)
; #define PG8_LDA(dst, b, h) do { _Pragma("unroll") for (int m = 0; m < 4; ++m) _Pragma("unroll") for (int k = 0; k < 2; ++k) dst[m][k] = *(const PG8_LAS bf16x8*)(lds + PG8_SA(b, h) + aoff + m * 2048 + k * 1024); } while (0)
; #define PG8_LDB(dst, b, h) do { _Pragma("unroll") for (int n = 0; n < 2; ++n) _Pragma("unroll") for (int k = 0; k < 2; ++k) dst[n][k] = *(const PG8_LAS bf16x8*)(lds + PG8_SB(b, h) + boff + n * 2048 + k * 1024); } while (0)
; #define PG8_MMA(ai, bj, At, Bt) do { __builtin_amdgcn_s_setprio(1); _Pragma("unroll") for (int m = 0; m < 4; ++m) _Pragma("unroll") for (int n = 0; n < 2; ++n) _Pragma("unroll") for (int k = 0; k < 2; ++k) \
;         acc[ai][bj][m][n] = __builtin_amdgcn_mfma_f32_16x16x32_bf16(Bt[n][k], At[m][k], acc[ai][bj][m][n], 0, 0, 0); __builtin_amdgcn_s_setprio(0); } while (0)
; #define PG8_WAIT_V(n) asm volatile("s_waitcnt vmcnt(" #n ")" ::: "memory")
; #define PG8_WAIT_L(n) asm volatile("s_waitcnt lgkmcnt(" #n ")" ::: "memory")
; #define PG8_BAR __builtin_amdgcn_s_barrier()
; #define PG8_SCHED __builtin_amdgcn_sched_barrier(0)
; template <class Epi, class Sched, bool ALIGN_EPI = false, bool SP2 = false>
; __device__ __forceinline__ void gemm_phase(PG8_LAS unsigned char* lds, const Gemm g, const Sched& S, const Epi& E, const int tid_in) {
;     ...
;             PG8_LDB(B0, 0, 0); PG8_LDB(B1, 0, 1); PG8_SCHED; PG8_LDA(At, 0, 0); PG8_STAGE(PG8_SA(1, 1), a1 + hstep, voffA);
;             PG8_WAIT_V(8); PG8_WAIT_L(0); PG8_BAR; PG8_MMA(0, 0, At, B0); PG8_MMA(0, 1, At, B1); PG8_BAR; PG8_SCHED;
;             PG8_LDA(At, 0, 1); PG8_STAGE(PG8_SB(0, 0), b2, voffB); PG8_STAGE(PG8_SB(0, 1), b2 + hstep, voffB); PG8_STAGE(PG8_SA(0, 0), a2, voffA);
.LBB0_139:
	s_add_i32 s50, s46, 2
	s_add_u32 s47, s44, s0
	s_addc_u32 s51, s45, s1
	s_add_u32 s52, s47, 0x100
	s_addc_u32 s47, s51, 0
	s_add_u32 s51, s48, s0
	s_addc_u32 s53, s49, s1
	s_add_i32 s73, 0, 0x10000
	s_cmp_eq_u32 s67, s46
	s_cselect_b32 s47, s23, s47
	s_cselect_b32 s46, s22, s52
	v_add_u32_e32 v0, s73, v222
	s_cselect_b32 s53, s43, s53
	s_cselect_b32 s52, s42, s51
	s_add_i32 s51, 0, 0x14000
	ds_read_b128 v[130:133], v0
	ds_read_b128 v[134:137], v0 offset:1024
	ds_read_b128 v[138:141], v0 offset:2048
	ds_read_b128 v[142:145], v0 offset:3072
	v_add_u32_e32 v0, s51, v222
	ds_read_b128 v[146:149], v0
	ds_read_b128 v[150:153], v0 offset:1024
	ds_read_b128 v[154:157], v0 offset:2048
	ds_read_b128 v[158:161], v0 offset:3072
	v_lshl_add_u64 v[234:235], v[208:209], 0, s[0:1]
	s_add_i32 m0, s58, 0xc000
	ds_read_b128 v[162:165], v231
	ds_read_b128 v[166:169], v231 offset:1024
	ds_read_b128 v[170:173], v231 offset:2048
	ds_read_b128 v[174:177], v231 offset:3072
	ds_read_b128 v[178:181], v231 offset:4096
	ds_read_b128 v[182:185], v231 offset:5120
	ds_read_b128 v[186:189], v231 offset:6144
	ds_read_b128 v[190:193], v231 offset:7168
	global_load_lds_dwordx4 v[234:235], off
	v_lshl_add_u64 v[234:235], v[210:211], 0, s[0:1]
	s_add_i32 m0, s58, 0xe000
	s_nop 0
	global_load_lds_dwordx4 v[234:235], off
	s_waitcnt vmcnt(8)
	s_waitcnt lgkmcnt(0)
	s_barrier
	v_mfma_f32_16x16x32_bf16 v[126:129], v[130:133], v[162:165], v[126:129]
	v_mfma_f32_16x16x32_bf16 v[122:125], v[138:141], v[162:165], v[122:125]
	v_mfma_f32_16x16x32_bf16 v[110:113], v[130:133], v[170:173], v[110:113]
	v_mfma_f32_16x16x32_bf16 v[106:109], v[138:141], v[170:173], v[106:109]
	v_mfma_f32_16x16x32_bf16 v[94:97], v[130:133], v[178:181], v[94:97]
	v_mfma_f32_16x16x32_bf16 v[90:93], v[138:141], v[178:181], v[90:93]
	v_mfma_f32_16x16x32_bf16 v[78:81], v[130:133], v[186:189], v[78:81]
	v_mfma_f32_16x16x32_bf16 v[74:77], v[138:141], v[186:189], v[74:77]
	v_mfma_f32_16x16x32_bf16 v[126:129], v[134:137], v[166:169], v[126:129]
	v_mfma_f32_16x16x32_bf16 v[122:125], v[142:145], v[166:169], v[122:125]
	v_mfma_f32_16x16x32_bf16 v[110:113], v[134:137], v[174:177], v[110:113]
	v_mfma_f32_16x16x32_bf16 v[106:109], v[142:145], v[174:177], v[106:109]
	v_mfma_f32_16x16x32_bf16 v[94:97], v[134:137], v[182:185], v[94:97]
	v_mfma_f32_16x16x32_bf16 v[90:93], v[142:145], v[182:185], v[90:93]
	v_mfma_f32_16x16x32_bf16 v[78:81], v[134:137], v[190:193], v[78:81]
	v_mfma_f32_16x16x32_bf16 v[74:77], v[142:145], v[190:193], v[74:77]
	v_mfma_f32_16x16x32_bf16 v[118:121], v[146:149], v[162:165], v[118:121]
	v_mfma_f32_16x16x32_bf16 v[114:117], v[154:157], v[162:165], v[114:117]
	v_mfma_f32_16x16x32_bf16 v[102:105], v[146:149], v[170:173], v[102:105]
	v_mfma_f32_16x16x32_bf16 v[98:101], v[154:157], v[170:173], v[98:101]
	v_mfma_f32_16x16x32_bf16 v[86:89], v[146:149], v[178:181], v[86:89]
	v_mfma_f32_16x16x32_bf16 v[82:85], v[154:157], v[178:181], v[82:85]
	v_mfma_f32_16x16x32_bf16 v[70:73], v[146:149], v[186:189], v[70:73]
	v_mfma_f32_16x16x32_bf16 v[66:69], v[154:157], v[186:189], v[66:69]
	v_mfma_f32_16x16x32_bf16 v[118:121], v[150:153], v[166:169], v[118:121]
	v_mfma_f32_16x16x32_bf16 v[114:117], v[158:161], v[166:169], v[114:117]
	v_mfma_f32_16x16x32_bf16 v[102:105], v[150:153], v[174:177], v[102:105]
	v_mfma_f32_16x16x32_bf16 v[98:101], v[158:161], v[174:177], v[98:101]
	v_mfma_f32_16x16x32_bf16 v[86:89], v[150:153], v[182:185], v[86:89]
	v_mfma_f32_16x16x32_bf16 v[82:85], v[158:161], v[182:185], v[82:85]
	v_mfma_f32_16x16x32_bf16 v[70:73], v[150:153], v[190:193], v[70:73]
	v_mfma_f32_16x16x32_bf16 v[66:69], v[158:161], v[190:193], v[66:69]
	s_barrier
	s_add_i32 s73, s73, s57
	v_lshl_add_u64 v[234:235], s[52:53], 0, v[198:199]
	s_mov_b32 m0, s73
	ds_read_b128 v[162:165], v231 offset:16384
	ds_read_b128 v[166:169], v231 offset:17408
	ds_read_b128 v[170:173], v231 offset:18432
	ds_read_b128 v[174:177], v231 offset:19456
	ds_read_b128 v[178:181], v231 offset:20480
	ds_read_b128 v[182:185], v231 offset:21504
	ds_read_b128 v[186:189], v231 offset:22528
	ds_read_b128 v[190:193], v231 offset:23552
	global_load_lds_dwordx4 v[234:235], off
	s_add_i32 m0, s73, 0x2000
	v_lshl_add_u64 v[236:237], s[52:53], 0, v[202:203]
	s_add_u32 s52, s52, s34
	s_addc_u32 s53, s53, 0
	s_add_i32 s51, s51, s57
	global_load_lds_dwordx4 v[236:237], off
	v_lshl_add_u64 v[238:239], s[52:53], 0, v[198:199]
	s_mov_b32 m0, s51
	v_lshl_add_u64 v[240:241], s[52:53], 0, v[202:203]
	global_load_lds_dwordx4 v[238:239], off
	s_add_i32 m0, s51, 0x2000
	v_lshl_add_u64 v[242:243], s[46:47], 0, v[196:197]
	global_load_lds_dwordx4 v[240:241], off
	s_mov_b32 m0, s58
	v_lshl_add_u64 v[244:245], s[46:47], 0, v[200:201]
	global_load_lds_dwordx4 v[242:243], off
	s_mov_b32 m0, s59
	s_nop 0
	global_load_lds_dwordx4 v[244:245], off
	s_waitcnt vmcnt(8)
	s_waitcnt lgkmcnt(0)
	s_barrier
; #define PG8_STAGE(bufoff, gbase, voff) do { _Pragma("unroll") for (int _i = 0; _i < 2; ++_i) \
;         __builtin_amdgcn_global_load_lds((const unsigned*)((const char*)(gbase) + (voff)[_i]), (PG8_LAS unsigned*)(lds + (bufoff) + ldsw + _i * 8192), 16, 0, 0); } while (0)
; #define PG8_LDA(dst, b, h) do { _Pragma("unroll") for (int m = 0; m < 4; ++m) _Pragma("unroll") for (int k = 0; k < 2; ++k) dst[m][k] = *(const PG8_LAS bf16x8*)(lds + PG8_SA(b, h) + aoff + m * 2048 + k * 1024); } while (0)
; #define PG8_LDB(dst, b, h) do { _Pragma("unroll") for (int n = 0; n < 2; ++n) _Pragma("unroll") for (int k = 0; k < 2; ++k) dst[n][k] = *(const PG8_LAS bf16x8*)(lds + PG8_SB(b, h) + boff + n * 2048 + k * 1024); } while (0)
; #define PG8_MMA(ai, bj, At, Bt) do { __builtin_amdgcn_s_setprio(1); _Pragma("unroll") for (int m = 0; m < 4; ++m) _Pragma("unroll") for (int n = 0; n < 2; ++n) _Pragma("unroll") for (int k = 0; k < 2; ++k) \
;         acc[ai][bj][m][n] = __builtin_amdgcn_mfma_f32_16x16x32_bf16(Bt[n][k], At[m][k], acc[ai][bj][m][n], 0, 0, 0); __builtin_amdgcn_s_setprio(0); } while (0)
; #define PG8_WAIT_V(n) asm volatile("s_waitcnt vmcnt(" #n ")" ::: "memory")
; #define PG8_WAIT_L(n) asm volatile("s_waitcnt lgkmcnt(" #n ")" ::: "memory")
; #define PG8_BAR __builtin_amdgcn_s_barrier()
; #define PG8_SCHED __builtin_amdgcn_sched_barrier(0)
; template <class Epi, class Sched, bool ALIGN_EPI = false, bool SP2 = false>
; __device__ __forceinline__ void gemm_phase(PG8_LAS unsigned char* lds, const Gemm g, const Sched& S, const Epi& E, const int tid_in) {
;     ...
;             PG8_WAIT_V(8); PG8_WAIT_L(0); PG8_BAR; PG8_MMA(1, 0, At, B0); PG8_MMA(1, 1, At, B1); PG8_BAR; PG8_SCHED;
;             PG8_LDB(B0, 1, 0); PG8_LDB(B1, 1, 1); PG8_SCHED; PG8_LDA(At, 1, 0); PG8_STAGE(PG8_SA(0, 1), a2 + hstep, voffA);
;             PG8_WAIT_V(8); PG8_WAIT_L(0); PG8_BAR; PG8_MMA(0, 0, At, B0); PG8_MMA(0, 1, At, B1); PG8_BAR; PG8_SCHED;
	v_mfma_f32_16x16x32_bf16 v[62:65], v[130:133], v[162:165], v[62:65]
	v_mfma_f32_16x16x32_bf16 v[58:61], v[138:141], v[162:165], v[58:61]
	v_mfma_f32_16x16x32_bf16 v[46:49], v[130:133], v[170:173], v[46:49]
	v_mfma_f32_16x16x32_bf16 v[42:45], v[138:141], v[170:173], v[42:45]
	v_mfma_f32_16x16x32_bf16 v[30:33], v[130:133], v[178:181], v[30:33]
	v_mfma_f32_16x16x32_bf16 v[26:29], v[138:141], v[178:181], v[26:29]
	v_mfma_f32_16x16x32_bf16 v[14:17], v[130:133], v[186:189], v[14:17]
	v_mfma_f32_16x16x32_bf16 v[10:13], v[138:141], v[186:189], v[10:13]
	v_mfma_f32_16x16x32_bf16 v[62:65], v[134:137], v[166:169], v[62:65]
	v_mfma_f32_16x16x32_bf16 v[58:61], v[142:145], v[166:169], v[58:61]
	v_mfma_f32_16x16x32_bf16 v[46:49], v[134:137], v[174:177], v[46:49]
	v_mfma_f32_16x16x32_bf16 v[42:45], v[142:145], v[174:177], v[42:45]
	v_mfma_f32_16x16x32_bf16 v[30:33], v[134:137], v[182:185], v[30:33]
	v_mfma_f32_16x16x32_bf16 v[26:29], v[142:145], v[182:185], v[26:29]
	v_mfma_f32_16x16x32_bf16 v[14:17], v[134:137], v[190:193], v[14:17]
	v_mfma_f32_16x16x32_bf16 v[10:13], v[142:145], v[190:193], v[10:13]
	v_mfma_f32_16x16x32_bf16 v[54:57], v[146:149], v[162:165], v[54:57]
	v_mfma_f32_16x16x32_bf16 v[50:53], v[154:157], v[162:165], v[50:53]
	v_mfma_f32_16x16x32_bf16 v[38:41], v[146:149], v[170:173], v[38:41]
	v_mfma_f32_16x16x32_bf16 v[34:37], v[154:157], v[170:173], v[34:37]
	v_mfma_f32_16x16x32_bf16 v[22:25], v[146:149], v[178:181], v[22:25]
	v_mfma_f32_16x16x32_bf16 v[18:21], v[154:157], v[178:181], v[18:21]
	v_mfma_f32_16x16x32_bf16 v[6:9], v[146:149], v[186:189], v[6:9]
	v_mfma_f32_16x16x32_bf16 v[2:5], v[154:157], v[186:189], v[2:5]
	v_mfma_f32_16x16x32_bf16 v[54:57], v[150:153], v[166:169], v[54:57]
	v_mfma_f32_16x16x32_bf16 v[50:53], v[158:161], v[166:169], v[50:53]
	v_mfma_f32_16x16x32_bf16 v[38:41], v[150:153], v[174:177], v[38:41]
	v_mfma_f32_16x16x32_bf16 v[34:37], v[158:161], v[174:177], v[34:37]
	v_mfma_f32_16x16x32_bf16 v[22:25], v[150:153], v[182:185], v[22:25]
	v_mfma_f32_16x16x32_bf16 v[18:21], v[158:161], v[182:185], v[18:21]
	v_mfma_f32_16x16x32_bf16 v[6:9], v[150:153], v[190:193], v[6:9]
	v_mfma_f32_16x16x32_bf16 v[2:5], v[158:161], v[190:193], v[2:5]
	s_barrier
	s_add_i32 s51, 0, 0x18000
	v_add_u32_e32 v0, s51, v222
	s_add_i32 s52, 0, 0x1c000
	ds_read_b128 v[130:133], v0
	ds_read_b128 v[134:137], v0 offset:1024
	ds_read_b128 v[138:141], v0 offset:2048
	ds_read_b128 v[142:145], v0 offset:3072
	v_add_u32_e32 v0, s52, v222
	ds_read_b128 v[146:149], v0
	ds_read_b128 v[150:153], v0 offset:1024
	ds_read_b128 v[154:157], v0 offset:2048
	ds_read_b128 v[158:161], v0 offset:3072
	s_add_u32 s46, s46, s34
	s_addc_u32 s47, s47, 0
	s_mov_b32 m0, s60
	v_lshl_add_u64 v[246:247], s[46:47], 0, v[196:197]
	ds_read_b128 v[162:165], v231 offset:32768
	ds_read_b128 v[166:169], v231 offset:33792
	ds_read_b128 v[170:173], v231 offset:34816
	ds_read_b128 v[174:177], v231 offset:35840
	ds_read_b128 v[178:181], v231 offset:36864
	ds_read_b128 v[182:185], v231 offset:37888
	ds_read_b128 v[186:189], v231 offset:38912
	ds_read_b128 v[190:193], v231 offset:39936
	global_load_lds_dwordx4 v[246:247], off
	v_lshl_add_u64 v[246:247], s[46:47], 0, v[200:201]
	s_mov_b32 m0, s61
	s_nop 0
	global_load_lds_dwordx4 v[246:247], off
	s_waitcnt vmcnt(8)
	s_waitcnt lgkmcnt(0)
	s_barrier
	v_mfma_f32_16x16x32_bf16 v[126:129], v[130:133], v[162:165], v[126:129]
	v_mfma_f32_16x16x32_bf16 v[122:125], v[138:141], v[162:165], v[122:125]
	v_mfma_f32_16x16x32_bf16 v[110:113], v[130:133], v[170:173], v[110:113]
	v_mfma_f32_16x16x32_bf16 v[106:109], v[138:141], v[170:173], v[106:109]
	v_mfma_f32_16x16x32_bf16 v[94:97], v[130:133], v[178:181], v[94:97]
	v_mfma_f32_16x16x32_bf16 v[90:93], v[138:141], v[178:181], v[90:93]
	v_mfma_f32_16x16x32_bf16 v[78:81], v[130:133], v[186:189], v[78:81]
	v_mfma_f32_16x16x32_bf16 v[74:77], v[138:141], v[186:189], v[74:77]
	v_mfma_f32_16x16x32_bf16 v[126:129], v[134:137], v[166:169], v[126:129]
	v_mfma_f32_16x16x32_bf16 v[122:125], v[142:145], v[166:169], v[122:125]
	v_mfma_f32_16x16x32_bf16 v[110:113], v[134:137], v[174:177], v[110:113]
	v_mfma_f32_16x16x32_bf16 v[106:109], v[142:145], v[174:177], v[106:109]
	v_mfma_f32_16x16x32_bf16 v[94:97], v[134:137], v[182:185], v[94:97]
	v_mfma_f32_16x16x32_bf16 v[90:93], v[142:145], v[182:185], v[90:93]
	v_mfma_f32_16x16x32_bf16 v[78:81], v[134:137], v[190:193], v[78:81]
	v_mfma_f32_16x16x32_bf16 v[74:77], v[142:145], v[190:193], v[74:77]
	v_mfma_f32_16x16x32_bf16 v[118:121], v[146:149], v[162:165], v[118:121]
	v_mfma_f32_16x16x32_bf16 v[114:117], v[154:157], v[162:165], v[114:117]
	v_mfma_f32_16x16x32_bf16 v[102:105], v[146:149], v[170:173], v[102:105]
	v_mfma_f32_16x16x32_bf16 v[98:101], v[154:157], v[170:173], v[98:101]
	v_mfma_f32_16x16x32_bf16 v[86:89], v[146:149], v[178:181], v[86:89]
	v_mfma_f32_16x16x32_bf16 v[82:85], v[154:157], v[178:181], v[82:85]
	v_mfma_f32_16x16x32_bf16 v[70:73], v[146:149], v[186:189], v[70:73]
	v_mfma_f32_16x16x32_bf16 v[66:69], v[154:157], v[186:189], v[66:69]
	v_mfma_f32_16x16x32_bf16 v[118:121], v[150:153], v[166:169], v[118:121]
	v_mfma_f32_16x16x32_bf16 v[114:117], v[158:161], v[166:169], v[114:117]
	v_mfma_f32_16x16x32_bf16 v[102:105], v[150:153], v[174:177], v[102:105]
	v_mfma_f32_16x16x32_bf16 v[98:101], v[158:161], v[174:177], v[98:101]
	v_mfma_f32_16x16x32_bf16 v[86:89], v[150:153], v[182:185], v[86:89]
	v_mfma_f32_16x16x32_bf16 v[82:85], v[158:161], v[182:185], v[82:85]
	v_mfma_f32_16x16x32_bf16 v[70:73], v[150:153], v[190:193], v[70:73]
	v_mfma_f32_16x16x32_bf16 v[66:69], v[158:161], v[190:193], v[66:69]
	s_barrier
; #define PG8_STAGE(bufoff, gbase, voff) do { _Pragma("unroll") for (int _i = 0; _i < 2; ++_i) \
;         __builtin_amdgcn_global_load_lds((const unsigned*)((const char*)(gbase) + (voff)[_i]), (PG8_LAS unsigned*)(lds + (bufoff) + ldsw + _i * 8192), 16, 0, 0); } while (0)
; #define PG8_LDA(dst, b, h) do { _Pragma("unroll") for (int m = 0; m < 4; ++m) _Pragma("unroll") for (int k = 0; k < 2; ++k) dst[m][k] = *(const PG8_LAS bf16x8*)(lds + PG8_SA(b, h) + aoff + m * 2048 + k * 1024); } while (0)
; #define PG8_MMA(ai, bj, At, Bt) do { __builtin_amdgcn_s_setprio(1); _Pragma("unroll") for (int m = 0; m < 4; ++m) _Pragma("unroll") for (int n = 0; n < 2; ++n) _Pragma("unroll") for (int k = 0; k < 2; ++k) \
;         acc[ai][bj][m][n] = __builtin_amdgcn_mfma_f32_16x16x32_bf16(Bt[n][k], At[m][k], acc[ai][bj][m][n], 0, 0, 0); __builtin_amdgcn_s_setprio(0); } while (0)
; #define PG8_WAIT_V(n) asm volatile("s_waitcnt vmcnt(" #n ")" ::: "memory")
; #define PG8_WAIT_L(n) asm volatile("s_waitcnt lgkmcnt(" #n ")" ::: "memory")
; #define PG8_BAR __builtin_amdgcn_s_barrier()
; #define PG8_SCHED __builtin_amdgcn_sched_barrier(0)
; template <class Epi, class Sched, bool ALIGN_EPI = false, bool SP2 = false>
; __device__ __forceinline__ void gemm_phase(PG8_LAS unsigned char* lds, const Gemm g, const Sched& S, const Epi& E, const int tid_in) {
;     ...
;             PG8_LDA(At, 1, 1); PG8_STAGE(PG8_SB(1, 0), b3, voffB); PG8_STAGE(PG8_SB(1, 1), b3 + hstep, voffB); PG8_STAGE(PG8_SA(1, 0), a3, voffA);
;             PG8_WAIT_V(8); PG8_WAIT_L(0); PG8_BAR; PG8_MMA(1, 0, At, B0); PG8_MMA(1, 1, At, B1); PG8_BAR; PG8_SCHED;
	s_add_i32 s46, s51, s57
	v_lshl_add_u64 v[234:235], v[234:235], 0, s[36:37]
	s_mov_b32 m0, s46
	ds_read_b128 v[162:165], v231 offset:49152
	ds_read_b128 v[166:169], v231 offset:50176
	ds_read_b128 v[170:173], v231 offset:51200
	ds_read_b128 v[174:177], v231 offset:52224
	ds_read_b128 v[178:181], v231 offset:53248
	ds_read_b128 v[182:185], v231 offset:54272
	ds_read_b128 v[186:189], v231 offset:55296
	ds_read_b128 v[190:193], v231 offset:56320
	global_load_lds_dwordx4 v[234:235], off
	v_lshl_add_u64 v[234:235], v[236:237], 0, s[36:37]
	s_add_i32 m0, s46, 0x2000
	s_add_i32 s46, s52, s57
	global_load_lds_dwordx4 v[234:235], off
	v_lshl_add_u64 v[234:235], v[238:239], 0, s[36:37]
	s_mov_b32 m0, s46
	s_nop 0
	global_load_lds_dwordx4 v[234:235], off
	v_lshl_add_u64 v[234:235], v[240:241], 0, s[36:37]
	s_add_i32 m0, s46, 0x2000
	s_nop 0
	global_load_lds_dwordx4 v[234:235], off
	v_lshl_add_u64 v[234:235], v[242:243], 0, s[36:37]
	s_mov_b32 m0, s65
	s_nop 0
	global_load_lds_dwordx4 v[234:235], off
	v_lshl_add_u64 v[234:235], v[244:245], 0, s[36:37]
	s_mov_b32 m0, s66
	s_nop 0
	global_load_lds_dwordx4 v[234:235], off
	s_waitcnt vmcnt(8)
	s_waitcnt lgkmcnt(0)
	s_barrier
	v_mfma_f32_16x16x32_bf16 v[62:65], v[130:133], v[162:165], v[62:65]
	v_mfma_f32_16x16x32_bf16 v[58:61], v[138:141], v[162:165], v[58:61]
	v_mfma_f32_16x16x32_bf16 v[46:49], v[130:133], v[170:173], v[46:49]
	v_mfma_f32_16x16x32_bf16 v[42:45], v[138:141], v[170:173], v[42:45]
	v_mfma_f32_16x16x32_bf16 v[30:33], v[130:133], v[178:181], v[30:33]
	v_mfma_f32_16x16x32_bf16 v[26:29], v[138:141], v[178:181], v[26:29]
	v_mfma_f32_16x16x32_bf16 v[14:17], v[130:133], v[186:189], v[14:17]
	v_mfma_f32_16x16x32_bf16 v[10:13], v[138:141], v[186:189], v[10:13]
	v_mfma_f32_16x16x32_bf16 v[62:65], v[134:137], v[166:169], v[62:65]
	v_mfma_f32_16x16x32_bf16 v[58:61], v[142:145], v[166:169], v[58:61]
	v_mfma_f32_16x16x32_bf16 v[46:49], v[134:137], v[174:177], v[46:49]
	v_mfma_f32_16x16x32_bf16 v[42:45], v[142:145], v[174:177], v[42:45]
	v_mfma_f32_16x16x32_bf16 v[30:33], v[134:137], v[182:185], v[30:33]
	v_mfma_f32_16x16x32_bf16 v[26:29], v[142:145], v[182:185], v[26:29]
	v_mfma_f32_16x16x32_bf16 v[14:17], v[134:137], v[190:193], v[14:17]
	v_mfma_f32_16x16x32_bf16 v[10:13], v[142:145], v[190:193], v[10:13]
	v_mfma_f32_16x16x32_bf16 v[54:57], v[146:149], v[162:165], v[54:57]
	v_mfma_f32_16x16x32_bf16 v[50:53], v[154:157], v[162:165], v[50:53]
	v_mfma_f32_16x16x32_bf16 v[38:41], v[146:149], v[170:173], v[38:41]
	v_mfma_f32_16x16x32_bf16 v[34:37], v[154:157], v[170:173], v[34:37]
	v_mfma_f32_16x16x32_bf16 v[22:25], v[146:149], v[178:181], v[22:25]
	v_mfma_f32_16x16x32_bf16 v[18:21], v[154:157], v[178:181], v[18:21]
	v_mfma_f32_16x16x32_bf16 v[6:9], v[146:149], v[186:189], v[6:9]
	v_mfma_f32_16x16x32_bf16 v[2:5], v[154:157], v[186:189], v[2:5]
	v_mfma_f32_16x16x32_bf16 v[54:57], v[150:153], v[166:169], v[54:57]
	v_mfma_f32_16x16x32_bf16 v[50:53], v[158:161], v[166:169], v[50:53]
	v_mfma_f32_16x16x32_bf16 v[38:41], v[150:153], v[174:177], v[38:41]
	v_mfma_f32_16x16x32_bf16 v[34:37], v[158:161], v[174:177], v[34:37]
	v_mfma_f32_16x16x32_bf16 v[22:25], v[150:153], v[182:185], v[22:25]
	v_mfma_f32_16x16x32_bf16 v[18:21], v[158:161], v[182:185], v[18:21]
	v_mfma_f32_16x16x32_bf16 v[6:9], v[150:153], v[190:193], v[6:9]
	v_mfma_f32_16x16x32_bf16 v[2:5], v[158:161], v[190:193], v[2:5]
	s_barrier
	s_add_u32 s0, s0, 0x100
	s_addc_u32 s1, s1, 0
	s_cmp_ge_u32 s50, s63
	s_mov_b32 s46, s50
	s_cbranch_scc1 .LBB0_142
